# v82: nt hint on the 32 final-output f32 stores (never re-read in-kernel; streamed past the caches)
# baseline (speedup 1.0000x reference)
.LBB0_350:
	v_lshl_add_u64 v[6:7], v[146:147], 2, s[68:69]
	s_waitcnt lgkmcnt(0)
	global_load_dwordx4 v[10:13], v[6:7], off offset:16
	global_load_dwordx4 v[14:17], v[6:7], off
	global_load_dwordx4 v[2:5], v[6:7], off offset:528
	s_nop 0
	global_load_dwordx4 v[6:9], v[6:7], off offset:512
	s_nop 0
	global_load_dwordx4 v[204:207], v[176:177], off offset:48
	global_load_dwordx4 v[208:211], v[176:177], off offset:32
	global_load_dwordx4 v[212:215], v[176:177], off offset:16
	global_load_dwordx4 v[216:219], v[176:177], off
	s_mov_b32 s28, 0x800000
	s_mov_b32 s96, 0x800000
	s_mov_b64 s[50:51], -1
	s_waitcnt vmcnt(0)
	v_add_f32_e32 v208, v208, v209
	v_mov_b32_e32 v176, v213
	v_mov_b32_e32 v146, v217
	v_mov_b32_e32 v147, v218
	v_mov_b32_e32 v217, v219
	v_mov_b32_e32 v177, v214
	v_mov_b32_e32 v213, v215
	v_pk_add_f32 v[146:147], v[146:147], v[216:217]
	v_pk_add_f32 v[176:177], v[176:177], v[212:213]
	v_add_f32_e32 v146, v146, v147
	v_pk_add_f32 v[176:177], v[176:177], v[176:177] op_sel:[0,1] op_sel_hi:[1,0]
	v_add_f32_e32 v146, 0, v146
	v_add_f32_e32 v210, v210, v211
	v_mov_b32_e32 v147, v204
	v_mov_b32_e32 v177, v205
	v_mov_b32_e32 v209, v206
	v_mov_b32_e32 v211, v207
	v_pk_add_f32 v[146:147], v[146:147], v[176:177]
	v_pk_add_f32 v[176:177], v[208:209], v[210:211]
	s_nop 0
	v_pk_add_f32 v[146:147], v[146:147], v[176:177]
	s_nop 0
	v_add_f32_e32 v146, v146, v147
	v_fmamk_f32 v146, v146, 0x3a800000, v191
	v_cmp_gt_f32_e32 vcc, s28, v146
	v_mul_f32_e32 v147, 0x4b800000, v146
	s_nop 0
	v_cndmask_b32_e32 v146, v146, v147, vcc
	v_rsq_f32_e32 v146, v146
	s_nop 0
	v_mul_f32_e32 v147, 0x45800000, v146
	v_cndmask_b32_e32 v146, v146, v147, vcc
	v_pk_mul_f32 v[176:177], v[144:145], v[146:147] op_sel_hi:[1,0]
	v_pk_mul_f32 v[142:143], v[142:143], v[146:147] op_sel_hi:[1,0]
	v_pk_mul_f32 v[122:123], v[122:123], v[146:147] op_sel_hi:[1,0]
	v_pk_mul_f32 v[144:145], v[16:17], v[142:143]
	v_pk_mul_f32 v[142:143], v[14:15], v[176:177]
	global_store_dwordx4 v[140:141], v[142:145], off nt
	v_pk_mul_f32 v[120:121], v[120:121], v[146:147] op_sel_hi:[1,0]
	v_pk_mul_f32 v[116:117], v[116:117], v[146:147] op_sel_hi:[1,0]
	v_pk_mul_f32 v[142:143], v[124:125], v[146:147] op_sel_hi:[1,0]
	v_pk_mul_f32 v[124:125], v[12:13], v[122:123]
	v_pk_mul_f32 v[122:123], v[10:11], v[142:143]
	global_store_dwordx4 v[140:141], v[122:125], off offset:16 nt
	s_nop 1
	v_pk_mul_f32 v[124:125], v[126:127], v[146:147] op_sel_hi:[1,0]
	v_pk_mul_f32 v[122:123], v[8:9], v[120:121]
	v_pk_mul_f32 v[120:121], v[6:7], v[124:125]
	global_store_dwordx4 v[140:141], v[120:123], off offset:512 nt
	s_nop 1
	v_pk_mul_f32 v[120:121], v[118:119], v[146:147] op_sel_hi:[1,0]
	v_pk_mul_f32 v[118:119], v[4:5], v[116:117]
	v_pk_mul_f32 v[116:117], v[2:3], v[120:121]
	global_store_dwordx4 v[140:141], v[116:119], off offset:528 nt
	global_load_dwordx4 v[116:119], v[174:175], off offset:48
	s_nop 0
	global_load_dwordx4 v[120:123], v[174:175], off offset:32
	global_load_dwordx4 v[124:127], v[174:175], off offset:16
	global_load_dwordx4 v[140:143], v[174:175], off
	s_waitcnt vmcnt(2)
	v_add_f32_e32 v120, v120, v121
	v_add_f32_e32 v122, v122, v123
	s_waitcnt vmcnt(0)
	v_mov_b32_e32 v144, v141
	v_mov_b32_e32 v145, v142
	v_mov_b32_e32 v141, v143
	v_mov_b32_e32 v142, v125
	v_mov_b32_e32 v143, v126
	v_mov_b32_e32 v125, v127
	v_pk_add_f32 v[140:141], v[144:145], v[140:141]
	v_pk_add_f32 v[124:125], v[142:143], v[124:125]
	v_add_f32_e32 v140, v140, v141
	v_pk_add_f32 v[124:125], v[124:125], v[124:125] op_sel:[0,1] op_sel_hi:[1,0]
	v_add_f32_e32 v140, 0, v140
	v_mov_b32_e32 v141, v116
	v_mov_b32_e32 v125, v117
	v_mov_b32_e32 v121, v118
	v_mov_b32_e32 v123, v119
	v_pk_add_f32 v[116:117], v[140:141], v[124:125]
	v_pk_add_f32 v[118:119], v[120:121], v[122:123]
	s_nop 0
	v_pk_add_f32 v[116:117], v[116:117], v[118:119]
	s_nop 0
	v_add_f32_e32 v116, v116, v117
	v_fmamk_f32 v116, v116, 0x3a800000, v191
	v_cmp_gt_f32_e32 vcc, s28, v116
	v_mul_f32_e32 v117, 0x4b800000, v116
	s_nop 0
	v_cndmask_b32_e32 v116, v116, v117, vcc
	v_rsq_f32_e32 v116, v116
	s_nop 0
	v_mul_f32_e32 v117, 0x45800000, v116
	v_cndmask_b32_e32 v116, v116, v117, vcc
	v_pk_mul_f32 v[106:107], v[106:107], v[116:117] op_sel_hi:[1,0]
	v_pk_mul_f32 v[108:109], v[108:109], v[116:117] op_sel_hi:[1,0]
	v_pk_mul_f32 v[106:107], v[10:11], v[106:107]
	v_pk_mul_f32 v[108:109], v[12:13], v[108:109]
	global_store_dwordx4 v[114:115], v[106:109], off offset:16 nt
	v_pk_mul_f32 v[104:105], v[104:105], v[116:117] op_sel_hi:[1,0]
	v_pk_mul_f32 v[110:111], v[110:111], v[116:117] op_sel_hi:[1,0]
	v_pk_mul_f32 v[108:109], v[128:129], v[116:117] op_sel_hi:[1,0]
	v_pk_mul_f32 v[106:107], v[8:9], v[104:105]
	v_pk_mul_f32 v[104:105], v[6:7], v[108:109]
	v_pk_mul_f32 v[112:113], v[112:113], v[116:117] op_sel_hi:[1,0]
	global_store_dwordx4 v[114:115], v[104:107], off offset:512 nt
	v_pk_mul_f32 v[100:101], v[100:101], v[116:117] op_sel_hi:[1,0]
	v_pk_mul_f32 v[112:113], v[16:17], v[112:113]
	v_pk_mul_f32 v[104:105], v[102:103], v[116:117] op_sel_hi:[1,0]
	v_pk_mul_f32 v[110:111], v[14:15], v[110:111]
	v_pk_mul_f32 v[102:103], v[4:5], v[100:101]
	v_pk_mul_f32 v[100:101], v[2:3], v[104:105]
	global_store_dwordx4 v[114:115], v[110:113], off nt
	global_store_dwordx4 v[114:115], v[100:103], off offset:528 nt
	global_load_dwordx4 v[100:103], v[178:179], off offset:48
	global_load_dwordx4 v[104:107], v[178:179], off offset:32
	global_load_dwordx4 v[108:111], v[178:179], off offset:16
	global_load_dwordx4 v[112:115], v[178:179], off
	s_waitcnt vmcnt(2)
	v_add_f32_e32 v104, v104, v105
	v_add_f32_e32 v106, v106, v107
	s_waitcnt vmcnt(0)
	v_mov_b32_e32 v116, v113
	v_mov_b32_e32 v117, v114
	v_mov_b32_e32 v113, v115
	v_mov_b32_e32 v114, v109
	v_mov_b32_e32 v115, v110
	v_mov_b32_e32 v109, v111
	v_pk_add_f32 v[112:113], v[116:117], v[112:113]
	v_pk_add_f32 v[108:109], v[114:115], v[108:109]
	v_add_f32_e32 v112, v112, v113
	v_pk_add_f32 v[108:109], v[108:109], v[108:109] op_sel:[0,1] op_sel_hi:[1,0]
	v_add_f32_e32 v112, 0, v112
	v_mov_b32_e32 v113, v100
	v_mov_b32_e32 v109, v101
	v_mov_b32_e32 v105, v102
	v_mov_b32_e32 v107, v103
	v_pk_add_f32 v[100:101], v[112:113], v[108:109]
	v_pk_add_f32 v[102:103], v[104:105], v[106:107]
	s_nop 0
	v_pk_add_f32 v[100:101], v[100:101], v[102:103]
	s_nop 0
	v_add_f32_e32 v100, v100, v101
	v_fmamk_f32 v100, v100, 0x3a800000, v191
	v_cmp_gt_f32_e32 vcc, s28, v100
	v_mul_f32_e32 v101, 0x4b800000, v100
	s_nop 0
	v_cndmask_b32_e32 v100, v100, v101, vcc
	v_rsq_f32_e32 v100, v100
	s_nop 0
	v_mul_f32_e32 v101, 0x45800000, v100
	v_cndmask_b32_e32 v100, v100, v101, vcc
	v_pk_mul_f32 v[90:91], v[90:91], v[100:101] op_sel_hi:[1,0]
	v_pk_mul_f32 v[92:93], v[92:93], v[100:101] op_sel_hi:[1,0]
	v_pk_mul_f32 v[90:91], v[10:11], v[90:91]
	v_pk_mul_f32 v[92:93], v[12:13], v[92:93]
	global_store_dwordx4 v[98:99], v[90:93], off offset:16 nt
	v_pk_mul_f32 v[88:89], v[88:89], v[100:101] op_sel_hi:[1,0]
	v_pk_mul_f32 v[94:95], v[94:95], v[100:101] op_sel_hi:[1,0]
	v_pk_mul_f32 v[92:93], v[148:149], v[100:101] op_sel_hi:[1,0]
	v_pk_mul_f32 v[90:91], v[8:9], v[88:89]
	v_pk_mul_f32 v[88:89], v[6:7], v[92:93]
	v_pk_mul_f32 v[96:97], v[96:97], v[100:101] op_sel_hi:[1,0]
	global_store_dwordx4 v[98:99], v[88:91], off offset:512 nt
	v_pk_mul_f32 v[84:85], v[84:85], v[100:101] op_sel_hi:[1,0]
	v_pk_mul_f32 v[96:97], v[16:17], v[96:97]
	v_pk_mul_f32 v[88:89], v[86:87], v[100:101] op_sel_hi:[1,0]
	v_pk_mul_f32 v[94:95], v[14:15], v[94:95]
	v_pk_mul_f32 v[86:87], v[4:5], v[84:85]
	v_pk_mul_f32 v[84:85], v[2:3], v[88:89]
	global_store_dwordx4 v[98:99], v[94:97], off nt
	global_store_dwordx4 v[98:99], v[84:87], off offset:528 nt
	global_load_dwordx4 v[84:87], v[180:181], off offset:48
	s_nop 0
	global_load_dwordx4 v[88:91], v[180:181], off offset:32
	global_load_dwordx4 v[92:95], v[180:181], off offset:16
	global_load_dwordx4 v[96:99], v[180:181], off
	s_waitcnt vmcnt(2)
	v_add_f32_e32 v88, v88, v89
	v_add_f32_e32 v90, v90, v91
	s_waitcnt vmcnt(0)
	v_mov_b32_e32 v100, v97
	v_mov_b32_e32 v101, v98
	v_mov_b32_e32 v97, v99
	v_mov_b32_e32 v98, v93
	v_mov_b32_e32 v99, v94
	v_mov_b32_e32 v93, v95
	v_pk_add_f32 v[96:97], v[100:101], v[96:97]
	v_pk_add_f32 v[92:93], v[98:99], v[92:93]
	v_add_f32_e32 v96, v96, v97
	v_pk_add_f32 v[92:93], v[92:93], v[92:93] op_sel:[0,1] op_sel_hi:[1,0]
	v_add_f32_e32 v96, 0, v96
	v_mov_b32_e32 v97, v84
	v_mov_b32_e32 v93, v85
	v_mov_b32_e32 v89, v86
	v_mov_b32_e32 v91, v87
	v_pk_add_f32 v[84:85], v[96:97], v[92:93]
	v_pk_add_f32 v[86:87], v[88:89], v[90:91]
	s_nop 0
	v_pk_add_f32 v[84:85], v[84:85], v[86:87]
	s_nop 0
	v_add_f32_e32 v84, v84, v85
	v_fmamk_f32 v84, v84, 0x3a800000, v191
	v_cmp_gt_f32_e32 vcc, s28, v84
	v_mul_f32_e32 v85, 0x4b800000, v84
	s_nop 0
	v_cndmask_b32_e32 v84, v84, v85, vcc
	v_rsq_f32_e32 v84, v84
	s_nop 0
	v_mul_f32_e32 v85, 0x45800000, v84
	v_cndmask_b32_e32 v84, v84, v85, vcc
	v_pk_mul_f32 v[74:75], v[74:75], v[84:85] op_sel_hi:[1,0]
	v_pk_mul_f32 v[76:77], v[76:77], v[84:85] op_sel_hi:[1,0]
	v_pk_mul_f32 v[74:75], v[10:11], v[74:75]
	v_pk_mul_f32 v[76:77], v[12:13], v[76:77]
	global_store_dwordx4 v[82:83], v[74:77], off offset:16 nt
	v_pk_mul_f32 v[72:73], v[72:73], v[84:85] op_sel_hi:[1,0]
	v_pk_mul_f32 v[78:79], v[78:79], v[84:85] op_sel_hi:[1,0]
	v_pk_mul_f32 v[76:77], v[150:151], v[84:85] op_sel_hi:[1,0]
	v_pk_mul_f32 v[74:75], v[8:9], v[72:73]
	v_pk_mul_f32 v[72:73], v[6:7], v[76:77]
	v_pk_mul_f32 v[80:81], v[80:81], v[84:85] op_sel_hi:[1,0]
	global_store_dwordx4 v[82:83], v[72:75], off offset:512 nt
	v_pk_mul_f32 v[68:69], v[68:69], v[84:85] op_sel_hi:[1,0]
	v_pk_mul_f32 v[80:81], v[16:17], v[80:81]
	v_pk_mul_f32 v[72:73], v[70:71], v[84:85] op_sel_hi:[1,0]
	v_pk_mul_f32 v[78:79], v[14:15], v[78:79]
	v_pk_mul_f32 v[70:71], v[4:5], v[68:69]
	v_pk_mul_f32 v[68:69], v[2:3], v[72:73]
	global_store_dwordx4 v[82:83], v[78:81], off nt
	global_store_dwordx4 v[82:83], v[68:71], off offset:528 nt
	global_load_dwordx4 v[68:71], v[182:183], off offset:48
	global_load_dwordx4 v[72:75], v[182:183], off offset:32
	global_load_dwordx4 v[76:79], v[182:183], off offset:16
	global_load_dwordx4 v[80:83], v[182:183], off
	s_waitcnt vmcnt(2)
	v_add_f32_e32 v72, v72, v73
	v_add_f32_e32 v74, v74, v75
	s_waitcnt vmcnt(0)
	v_mov_b32_e32 v84, v81
	v_mov_b32_e32 v85, v82
	v_mov_b32_e32 v81, v83
	v_mov_b32_e32 v82, v77
	v_mov_b32_e32 v83, v78
	v_mov_b32_e32 v77, v79
	v_pk_add_f32 v[80:81], v[84:85], v[80:81]
	v_pk_add_f32 v[76:77], v[82:83], v[76:77]
	v_add_f32_e32 v80, v80, v81
	v_pk_add_f32 v[76:77], v[76:77], v[76:77] op_sel:[0,1] op_sel_hi:[1,0]
	v_add_f32_e32 v80, 0, v80
	v_mov_b32_e32 v81, v68
	v_mov_b32_e32 v77, v69
	v_mov_b32_e32 v73, v70
	v_mov_b32_e32 v75, v71
	v_pk_add_f32 v[68:69], v[80:81], v[76:77]
	v_pk_add_f32 v[70:71], v[72:73], v[74:75]
	s_nop 0
	v_pk_add_f32 v[68:69], v[68:69], v[70:71]
	s_nop 0
	v_add_f32_e32 v68, v68, v69
	v_fmamk_f32 v68, v68, 0x3a800000, v191
	v_cmp_gt_f32_e32 vcc, s28, v68
	v_mul_f32_e32 v69, 0x4b800000, v68
	s_nop 0
	v_cndmask_b32_e32 v68, v68, v69, vcc
	v_rsq_f32_e32 v68, v68
	s_nop 0
	v_mul_f32_e32 v69, 0x45800000, v68
	v_cndmask_b32_e32 v68, v68, v69, vcc
	v_pk_mul_f32 v[58:59], v[58:59], v[68:69] op_sel_hi:[1,0]
	v_pk_mul_f32 v[60:61], v[60:61], v[68:69] op_sel_hi:[1,0]
	v_pk_mul_f32 v[58:59], v[10:11], v[58:59]
	v_pk_mul_f32 v[60:61], v[12:13], v[60:61]
	global_store_dwordx4 v[66:67], v[58:61], off offset:16 nt
	v_pk_mul_f32 v[56:57], v[56:57], v[68:69] op_sel_hi:[1,0]
	v_pk_mul_f32 v[62:63], v[62:63], v[68:69] op_sel_hi:[1,0]
	v_pk_mul_f32 v[60:61], v[152:153], v[68:69] op_sel_hi:[1,0]
	v_pk_mul_f32 v[58:59], v[8:9], v[56:57]
	v_pk_mul_f32 v[56:57], v[6:7], v[60:61]
	v_pk_mul_f32 v[64:65], v[64:65], v[68:69] op_sel_hi:[1,0]
	global_store_dwordx4 v[66:67], v[56:59], off offset:512 nt
	v_pk_mul_f32 v[52:53], v[52:53], v[68:69] op_sel_hi:[1,0]
	v_pk_mul_f32 v[64:65], v[16:17], v[64:65]
	v_pk_mul_f32 v[56:57], v[54:55], v[68:69] op_sel_hi:[1,0]
	v_pk_mul_f32 v[62:63], v[14:15], v[62:63]
	v_pk_mul_f32 v[54:55], v[4:5], v[52:53]
	v_pk_mul_f32 v[52:53], v[2:3], v[56:57]
	global_store_dwordx4 v[66:67], v[62:65], off nt
	global_store_dwordx4 v[66:67], v[52:55], off offset:528 nt
	global_load_dwordx4 v[52:55], v[184:185], off offset:48
	s_nop 0
	global_load_dwordx4 v[56:59], v[184:185], off offset:32
	global_load_dwordx4 v[60:63], v[184:185], off offset:16
	global_load_dwordx4 v[64:67], v[184:185], off
	s_waitcnt vmcnt(2)
	v_add_f32_e32 v56, v56, v57
	v_add_f32_e32 v58, v58, v59
	s_waitcnt vmcnt(0)
	v_mov_b32_e32 v68, v65
	v_mov_b32_e32 v69, v66
	v_mov_b32_e32 v65, v67
	v_mov_b32_e32 v66, v61
	v_mov_b32_e32 v67, v62
	v_mov_b32_e32 v61, v63
	v_pk_add_f32 v[64:65], v[68:69], v[64:65]
	v_pk_add_f32 v[60:61], v[66:67], v[60:61]
	v_add_f32_e32 v64, v64, v65
	v_pk_add_f32 v[60:61], v[60:61], v[60:61] op_sel:[0,1] op_sel_hi:[1,0]
	v_add_f32_e32 v64, 0, v64
	v_mov_b32_e32 v65, v52
	v_mov_b32_e32 v61, v53
	v_mov_b32_e32 v57, v54
	v_mov_b32_e32 v59, v55
	v_pk_add_f32 v[52:53], v[64:65], v[60:61]
	v_pk_add_f32 v[54:55], v[56:57], v[58:59]
	s_nop 0
	v_pk_add_f32 v[52:53], v[52:53], v[54:55]
	s_nop 0
	v_add_f32_e32 v52, v52, v53
	v_fmamk_f32 v52, v52, 0x3a800000, v191
	v_cmp_gt_f32_e32 vcc, s28, v52
	v_mul_f32_e32 v53, 0x4b800000, v52
	s_nop 0
	v_cndmask_b32_e32 v52, v52, v53, vcc
	v_rsq_f32_e32 v52, v52
	s_nop 0
	v_mul_f32_e32 v53, 0x45800000, v52
	v_cndmask_b32_e32 v52, v52, v53, vcc
	v_pk_mul_f32 v[42:43], v[42:43], v[52:53] op_sel_hi:[1,0]
	v_pk_mul_f32 v[44:45], v[44:45], v[52:53] op_sel_hi:[1,0]
	v_pk_mul_f32 v[42:43], v[10:11], v[42:43]
	v_pk_mul_f32 v[44:45], v[12:13], v[44:45]
	global_store_dwordx4 v[50:51], v[42:45], off offset:16 nt
	v_pk_mul_f32 v[46:47], v[46:47], v[52:53] op_sel_hi:[1,0]
	v_pk_mul_f32 v[48:49], v[48:49], v[52:53] op_sel_hi:[1,0]
	v_pk_mul_f32 v[42:43], v[158:159], v[52:53] op_sel_hi:[1,0]
	v_pk_mul_f32 v[44:45], v[154:155], v[52:53] op_sel_hi:[1,0]
	v_pk_mul_f32 v[42:43], v[6:7], v[42:43]
	v_pk_mul_f32 v[44:45], v[8:9], v[44:45]
	global_store_dwordx4 v[50:51], v[42:45], off offset:512 nt
	v_pk_mul_f32 v[38:39], v[38:39], v[52:53] op_sel_hi:[1,0]
	v_pk_mul_f32 v[48:49], v[16:17], v[48:49]
	v_pk_mul_f32 v[42:43], v[40:41], v[52:53] op_sel_hi:[1,0]
	v_pk_mul_f32 v[46:47], v[14:15], v[46:47]
	v_pk_mul_f32 v[40:41], v[4:5], v[38:39]
	v_pk_mul_f32 v[38:39], v[2:3], v[42:43]
	global_store_dwordx4 v[50:51], v[46:49], off nt
	global_store_dwordx4 v[50:51], v[38:41], off offset:528 nt
	global_load_dwordx4 v[38:41], v[186:187], off offset:48
	global_load_dwordx4 v[42:45], v[186:187], off offset:32
	global_load_dwordx4 v[46:49], v[186:187], off offset:16
	global_load_dwordx4 v[50:53], v[186:187], off
	s_waitcnt vmcnt(2)
	v_add_f32_e32 v42, v42, v43
	v_add_f32_e32 v44, v44, v45
	s_waitcnt vmcnt(0)
	v_mov_b32_e32 v54, v51
	v_mov_b32_e32 v55, v52
	v_mov_b32_e32 v51, v53
	v_mov_b32_e32 v52, v47
	v_mov_b32_e32 v53, v48
	v_mov_b32_e32 v47, v49
	v_pk_add_f32 v[50:51], v[54:55], v[50:51]
	v_pk_add_f32 v[46:47], v[52:53], v[46:47]
	v_add_f32_e32 v50, v50, v51
	v_pk_add_f32 v[46:47], v[46:47], v[46:47] op_sel:[0,1] op_sel_hi:[1,0]
	v_add_f32_e32 v50, 0, v50
	v_mov_b32_e32 v51, v38
	v_mov_b32_e32 v47, v39
	v_mov_b32_e32 v43, v40
	v_mov_b32_e32 v45, v41
	v_pk_add_f32 v[38:39], v[50:51], v[46:47]
	v_pk_add_f32 v[40:41], v[42:43], v[44:45]
	s_nop 0
	v_pk_add_f32 v[38:39], v[38:39], v[40:41]
	s_nop 0
	v_add_f32_e32 v38, v38, v39
	v_fmamk_f32 v38, v38, 0x3a800000, v191
	v_cmp_gt_f32_e32 vcc, s28, v38
	v_mul_f32_e32 v39, 0x4b800000, v38
	s_nop 0
	v_cndmask_b32_e32 v38, v38, v39, vcc
	v_rsq_f32_e32 v38, v38
	s_nop 0
	v_mul_f32_e32 v39, 0x45800000, v38
	v_cndmask_b32_e32 v38, v38, v39, vcc
	v_pk_mul_f32 v[26:27], v[26:27], v[38:39] op_sel_hi:[1,0]
	v_pk_mul_f32 v[28:29], v[28:29], v[38:39] op_sel_hi:[1,0]
	v_pk_mul_f32 v[26:27], v[10:11], v[26:27]
	v_pk_mul_f32 v[28:29], v[12:13], v[28:29]
	global_store_dwordx4 v[34:35], v[26:29], off offset:16 nt
	v_pk_mul_f32 v[30:31], v[30:31], v[38:39] op_sel_hi:[1,0]
	v_pk_mul_f32 v[32:33], v[32:33], v[38:39] op_sel_hi:[1,0]
	v_pk_mul_f32 v[26:27], v[166:167], v[38:39] op_sel_hi:[1,0]
	v_pk_mul_f32 v[28:29], v[162:163], v[38:39] op_sel_hi:[1,0]
	v_pk_mul_f32 v[26:27], v[6:7], v[26:27]
	v_pk_mul_f32 v[28:29], v[8:9], v[28:29]
	global_store_dwordx4 v[34:35], v[26:29], off offset:512 nt
	v_pk_mul_f32 v[32:33], v[16:17], v[32:33]
	v_pk_mul_f32 v[30:31], v[14:15], v[30:31]
	v_pk_mul_f32 v[26:27], v[160:161], v[38:39] op_sel_hi:[1,0]
	v_pk_mul_f32 v[28:29], v[156:157], v[38:39] op_sel_hi:[1,0]
	v_pk_mul_f32 v[26:27], v[2:3], v[26:27]
	v_pk_mul_f32 v[28:29], v[4:5], v[28:29]
	global_store_dwordx4 v[34:35], v[30:33], off nt
	global_store_dwordx4 v[34:35], v[26:29], off offset:528 nt
	global_load_dwordx4 v[26:29], v[188:189], off offset:48
	s_nop 0
	global_load_dwordx4 v[30:33], v[188:189], off offset:32
	global_load_dwordx4 v[38:41], v[188:189], off offset:16
	global_load_dwordx4 v[42:45], v[188:189], off
	s_waitcnt vmcnt(2)
	v_add_f32_e32 v30, v30, v31
	v_add_f32_e32 v32, v32, v33
	s_waitcnt vmcnt(0)
	v_mov_b32_e32 v34, v43
	v_mov_b32_e32 v35, v44
	v_mov_b32_e32 v43, v45
	v_pk_add_f32 v[34:35], v[34:35], v[42:43]
	v_mov_b32_e32 v42, v39
	v_mov_b32_e32 v43, v40
	v_mov_b32_e32 v39, v41
	v_pk_add_f32 v[38:39], v[42:43], v[38:39]
	v_add_f32_e32 v34, v34, v35
	v_pk_add_f32 v[38:39], v[38:39], v[38:39] op_sel:[0,1] op_sel_hi:[1,0]
	v_add_f32_e32 v34, 0, v34
	v_mov_b32_e32 v35, v26
	v_mov_b32_e32 v39, v27
	v_mov_b32_e32 v31, v28
	v_mov_b32_e32 v33, v29
	v_pk_add_f32 v[26:27], v[34:35], v[38:39]
	v_pk_add_f32 v[28:29], v[30:31], v[32:33]
	s_nop 0
	v_pk_add_f32 v[26:27], v[26:27], v[28:29]
	s_nop 0
	v_add_f32_e32 v26, v26, v27
	v_fmamk_f32 v26, v26, 0x3a800000, v191
	v_cmp_gt_f32_e32 vcc, s28, v26
	v_mul_f32_e32 v27, 0x4b800000, v26
	s_nop 0
	v_cndmask_b32_e32 v26, v26, v27, vcc
	v_rsq_f32_e32 v26, v26
	s_nop 0
	v_mul_f32_e32 v27, 0x45800000, v26
	v_cndmask_b32_e32 v26, v26, v27, vcc
	v_pk_mul_f32 v[28:29], v[36:37], v[26:27] op_sel_hi:[1,0]
	v_pk_mul_f32 v[24:25], v[24:25], v[26:27] op_sel_hi:[1,0]
	v_pk_mul_f32 v[14:15], v[14:15], v[28:29]
	v_pk_mul_f32 v[16:17], v[16:17], v[24:25]
	global_store_dwordx4 v[18:19], v[14:17], off nt
	s_andn2_b64 vcc, exec, s[48:49]
	s_nop 0
	v_pk_mul_f32 v[14:15], v[22:23], v[26:27] op_sel_hi:[1,0]
	v_pk_mul_f32 v[16:17], v[20:21], v[26:27] op_sel_hi:[1,0]
	v_pk_mul_f32 v[10:11], v[10:11], v[14:15]
	v_pk_mul_f32 v[12:13], v[12:13], v[16:17]
	global_store_dwordx4 v[18:19], v[10:13], off offset:16 nt
	s_nop 1
	v_pk_mul_f32 v[10:11], v[172:173], v[26:27] op_sel_hi:[1,0]
	v_pk_mul_f32 v[12:13], v[170:171], v[26:27] op_sel_hi:[1,0]
	v_pk_mul_f32 v[6:7], v[6:7], v[10:11]
	v_pk_mul_f32 v[8:9], v[8:9], v[12:13]
	global_store_dwordx4 v[18:19], v[6:9], off offset:512 nt
	s_nop 1
	v_pk_mul_f32 v[6:7], v[168:169], v[26:27] op_sel_hi:[1,0]
	v_pk_mul_f32 v[8:9], v[164:165], v[26:27] op_sel_hi:[1,0]
	v_pk_mul_f32 v[2:3], v[2:3], v[6:7]
	v_pk_mul_f32 v[4:5], v[4:5], v[8:9]
	global_store_dwordx4 v[18:19], v[2:5], off offset:528 nt
	s_cbranch_vccnz .LBB0_261
	v_readlane_b32 s28, v234, 9
	v_readlane_b32 s29, v234, 10
	s_andn2_b64 vcc, exec, s[28:29]
	s_cbranch_vccnz .LBB0_260
	s_barrier
	s_branch .LBB0_260
